# scan: all eight waves run gate then mma (same order) instead of opposite orders per wave half
# speedup vs baseline: 1.0167x; 1.0167x over previous
; #define LAS __attribute__((address_space(3)))
; #define SC_BAR() asm volatile("s_waitcnt lgkmcnt(0)\n\ts_barrier" ::: "memory")
; #define SC_LOFFC(c) SC_LOFF(((c) < 128 ? (c) : 128))
; __device__ __forceinline__ void scan_mfma_phase(const Params& p, LAS unsigned char* lds) {
;     ...
;     const int lane = tid_ & 63, w = __builtin_amdgcn_readfirstlane(tid_ >> 6), l16 = lane & 15, g = lane >> 4;
;     LAS unsigned char* buf0 = lds; LAS unsigned char* buf1 = lds + SC_BUF;
;     for (int item = blockIdx.x; item < NBATCH * 8; item += gridDim.x) {
;         const int b = item >> 3, h = item & 7, col = h * 128 + 16 * w + l16;
;         const float lb = 1.0f / (1.0f + __expf(p.lb_logits[1024 + col] - p.lb_logits[col])), gn = p.hg_norm_g[16 * w + l16];
;         f32x4 St[8];
; #pragma unroll
;         for (int kt = 0; kt < 8; ++kt) St[kt] = (f32x4){0.f, 0.f, 0.f, 0.f};
;     ...
;         const bf16* P0 = (tid_ >> 8) ? HF : HQ; const bf16* P1 = (tid_ >> 8) ? HG : (const bf16*)HIO;
;     ...
;         ScanRaw rawA, rawB; ScanSt st0, st1; f32x4 oprev = {0.f, 0.f, 0.f, 0.f};
;         scan_load(rawA, P0, P1, SC_LOFF(0)); scan_load(rawB, P0, P1, SC_LOFF(1));
;         scan_stage(rawA, SC_SLOT(0), tid_); scan_stage(rawB, SC_SLOT(1), tid_);
;         scan_load(rawB, P0, P1, SC_LOFF(2));
;         SC_BAR();
;         scan_gate(SC_SLOT(0), st0, buf0, lb, w, l16, g);
;         SC_BAR();
;         for (int i = 0; i < 130; i += 2) {
;             scan_load(rawA, P0, P1, SC_LOFFC(i + 3));
;             if (i >= 2) scan_finish(oprev, st1, buf1, HIO, SC_OFF(i - 1), gn, g);
;             if (w < 4) { scan_gate(SC_SLOT(i + 1), st1, buf1, lb, w, l16, g); scan_mma(St, st0, oprev, buf0, w, l16, g); }
;             else       { scan_mma(St, st0, oprev, buf0, w, l16, g); scan_gate(SC_SLOT(i + 1), st1, buf1, lb, w, l16, g); }
.LBB0_370:
	s_or_b64 exec, exec, s[0:1]
	v_mov_b32_e32 v2, v201
	s_waitcnt lgkmcnt(0)
	s_barrier
	s_cmpk_gt_i32 s2, 0xff
	v_readfirstlane_b32 s3, v2
	s_cbranch_scc1 .LBB0_446
	s_movk_i32 s0, 0x100
	v_mov_b32_e32 v0, 0x13200000
	v_mov_b32_e32 v1, 0xb100000
	v_cmp_gt_u32_e32 vcc, s0, v2
	v_mov_b32_e32 v6, s39
	v_bfe_u32 v111, v2, 4, 2
	v_cndmask_b32_e32 v0, v0, v1, vcc
	v_mov_b32_e32 v1, 0
	v_lshl_add_u64 v[106:107], s[28:29], 0, v[0:1]
	v_mov_b32_e32 v0, s41
	v_cndmask_b32_e32 v109, v0, v6, vcc
	v_mov_b32_e32 v0, s40
	v_mov_b32_e32 v6, s38
	v_cndmask_b32_e32 v108, v0, v6, vcc
	v_lshlrev_b32_e32 v6, 3, v2
	v_and_b32_e32 v112, 0x78, v6
	v_lshrrev_b32_e32 v6, 5, v2
	v_and_b32_e32 v6, 6, v6
	v_and_b32_e32 v3, 15, v2
	v_bfe_u32 v110, v2, 4, 4
	v_lshlrev_b32_e32 v7, 4, v2
	v_add_lshl_u32 v2, v6, v2, 4
	v_lshlrev_b32_e32 v139, 10, v111
	s_ashr_i32 s6, s3, 6
	v_and_b32_e32 v119, 0xf0, v2
	v_add_u32_e32 v2, 0, v139
	v_lshlrev_b32_e32 v6, 1, v3
	v_lshl_or_b32 v104, s6, 4, v3
	v_and_b32_e32 v113, 0xfffff000, v7
	v_and_b32_e32 v115, 0xf00, v7
	v_lshl_or_b32 v7, s6, 5, v6
	v_lshl_add_u32 v144, v111, 6, v2
	s_cmp_gt_i32 s6, 3
	s_movk_i32 s6, 0xfbc8
	v_add_u32_e32 v8, 0, v113
	v_and_b32_e32 v141, 14, v6
	v_lshlrev_b32_e32 v146, 3, v111
	v_mad_i32_i24 v6, v111, s6, v144
	v_lshlrev_b32_e32 v114, 2, v111
	v_mov_b32_e32 v4, s46
	v_mov_b32_e32 v5, s47
	v_ashrrev_i32_e32 v105, 31, v104
	v_add3_u32 v138, v8, v115, v119
	v_lshl_add_u32 v7, v111, 5, v7
	v_add_u32_e32 v148, v6, v146
	v_or_b32_e32 v8, 2, v114
	s_movk_i32 s16, 0x430
	v_lshlrev_b32_e32 v0, 10, v110
	v_and_b32_e32 v140, 0xf0, v7
	s_movk_i32 s7, 0xffe4
	v_cmp_gt_u32_e64 s[10:11], v8, v3
	v_or_b32_e32 v8, 3, v114
	v_mad_u32_u24 v149, v111, s16, v148
	v_lshl_add_u64 v[116:117], v[104:105], 2, v[4:5]
	s_brev_b32 s16, 32
	v_mbcnt_hi_u32_b32 v105, -1, v234
	v_add3_u32 v142, v2, v140, v141
	v_lshl_add_u32 v145, v104, 5, 0
	v_mul_lo_u32 v2, v104, s7
	s_mov_b64 s[46:47], 0
	v_mul_u32_u24_e32 v7, 0x110, v3
	v_cmp_gt_u32_e64 s[6:7], v114, v3
	v_cmp_lt_u32_e64 s[8:9], v114, v3
	v_cmp_gt_u32_e64 s[12:13], v8, v3
	v_lshlrev_b32_e32 v8, 5, v3
	v_cmp_eq_u32_e64 s[14:15], 0, v3
	s_andn2_b32 s3, s3, 63
	v_mul_i32_i24_e32 v3, 0xfffffbd0, v111
	v_or3_b32 v118, v0, v112, s16
	v_and_b32_e32 v0, 64, v105
	s_mov_b32 s43, 0
	v_cmp_eq_u32_e64 s[0:1], 0, v111
	v_cmp_ne_u32_e64 s[4:5], 0, v111
	v_lshlrev_b32_e32 v143, 1, v104
	v_lshlrev_b32_e32 v147, 4, v111
	s_add_i32 s3, s3, 0
	v_xor_b32_e32 v150, 16, v105
	v_mov_b32_e32 v151, 0x358637bd
	v_add_u32_e32 v152, v149, v3
	v_add_u32_e32 v153, 64, v0
	v_xor_b32_e32 v154, 32, v105
	v_add_u32_e32 v155, v145, v2
	v_add_u32_e32 v156, v6, v7
	v_add_u32_e32 v157, v6, v8
	s_mov_b32 s48, s2
	s_branch .LBB0_373
